# final phase (LN2 + output) stores marked sc1 write-through so the end-of-kernel L2 flush has less to drain; rest identical to the dry-queue-skip build
# speedup vs baseline: 1.0091x; 1.0011x over previous
; #define PG8_LAS __attribute__((address_space(3)))
; __device__ __forceinline__ unsigned cvt_pk_bf16(float lo, float hi) { f32x2c_t v = {lo, hi}; bf16x2c_t b = __builtin_convertvector(v, bf16x2c_t); return __builtin_bit_cast(unsigned, b); }
;     __device__ __forceinline__ void fused(f32x4 (&acc)[2][2][4][2], const Unit& u, int wr, int wc, int fr, int fq, PG8_LAS unsigned char* lds, int wid, int lane) const {
;     ...
; #pragma unroll
;         for (int bj = 0; bj < 2; ++bj)
; #pragma unroll
;             for (int n = 0; n < 2; ++n) { const int c = col0 + bj * HALF + n * 16; const f32x4 g4 = *(const f32x4*)(gam + c), b4 = *(const f32x4*)(bet + c);
; #pragma unroll
;                 for (int ai = 0; ai < 2; ++ai)
; #pragma unroll
;                     for (int m = 0; m < 4; ++m) { const int r = ai * HALF + wr * 64 + m * 16 + fr; const f32x2v sr = S[r]; const size_t o = (size_t)(u.pm * BM + r) * ldc + c;
;                         f32x4 v = (acc[ai][bj][m][n] - sr.x) * sr.y * g4 + b4; if (bad) v = (f32x4){qnan, qnan, qnan, qnan};
;                         if (OUT_BF16) { u32x2v w; w.x = cvt_pk_bf16(v[0], v[1]); w.y = cvt_pk_bf16(v[2], v[3]); *(PG8_LAS u32x2v*)(lds + 16384 + r * 528 + (c - u.pn * BM) * 2) = w; }
;                         else *(f32x4*)((float*)out + o) = v; } }
.LBB0_919:
	s_or_b64 exec, exec, s[2:3]
	v_lshlrev_b64 v[158:159], 2, v[128:129]
	s_waitcnt lgkmcnt(0)
	s_barrier
	v_lshl_add_u64 v[148:149], s[62:63], 0, v[158:159]
	v_lshl_add_u64 v[150:151], s[64:65], 0, v[158:159]
	global_load_dwordx4 v[140:143], v[148:149], off
	global_load_dwordx4 v[144:147], v[150:151], off
	v_lshl_add_u32 v128, v152, 3, 0
	v_add_u32_e32 v170, 0x2000, v128
	ds_read2_b64 v[136:139], v170 offset1:16
	ds_read2_b64 v[132:135], v170 offset0:32 offset1:48
	ds_read2_b64 v[128:131], v170 offset0:128 offset1:144
	v_add_u32_e32 v160, s16, v152
	v_ashrrev_i32_e32 v161, 31, v160
	v_add_u32_e32 v152, 16, v160
	v_add_u32_e32 v154, 32, v160
	s_waitcnt lgkmcnt(2)
	v_sub_f32_e32 v107, v107, v136
	v_sub_f32_e32 v106, v106, v136
	v_sub_f32_e32 v105, v105, v136
	v_sub_f32_e32 v104, v104, v136
	v_add_u32_e32 v156, 48, v160
	v_lshlrev_b64 v[164:165], 12, v[160:161]
	v_ashrrev_i32_e32 v153, 31, v152
	v_ashrrev_i32_e32 v155, 31, v154
	v_sub_f32_e32 v119, v119, v138
	v_sub_f32_e32 v118, v118, v138
	v_sub_f32_e32 v117, v117, v138
	v_sub_f32_e32 v116, v116, v138
	s_waitcnt lgkmcnt(1)
	v_sub_f32_e32 v127, v127, v132
	v_sub_f32_e32 v126, v126, v132
	v_sub_f32_e32 v125, v125, v132
	v_sub_f32_e32 v124, v124, v132
	v_pk_mul_f32 v[104:105], v[136:137], v[104:105] op_sel:[1,0]
	v_pk_mul_f32 v[106:107], v[136:137], v[106:107] op_sel:[1,0]
	v_mov_b32_e32 v162, 0x7fc00000
	v_ashrrev_i32_e32 v157, 31, v156
	v_lshl_add_u64 v[164:165], s[66:67], 0, v[164:165]
	v_lshlrev_b64 v[152:153], 12, v[152:153]
	v_lshlrev_b64 v[154:155], 12, v[154:155]
	v_sub_f32_e32 v123, v123, v134
	v_sub_f32_e32 v122, v122, v134
	v_sub_f32_e32 v121, v121, v134
	v_sub_f32_e32 v120, v120, v134
	v_pk_mul_f32 v[116:117], v[138:139], v[116:117] op_sel:[1,0]
	v_pk_mul_f32 v[118:119], v[138:139], v[118:119] op_sel:[1,0]
	v_pk_mul_f32 v[124:125], v[132:133], v[124:125] op_sel:[1,0]
	v_pk_mul_f32 v[126:127], v[132:133], v[126:127] op_sel:[1,0]
	v_cmp_eq_u32_e32 vcc, 0, v163
	v_lshlrev_b64 v[166:167], 12, v[156:157]
	v_lshl_add_u64 v[156:157], v[164:165], 0, v[158:159]
	v_lshl_add_u64 v[152:153], s[66:67], 0, v[152:153]
	v_lshl_add_u64 v[164:165], s[66:67], 0, v[154:155]
	v_pk_mul_f32 v[120:121], v[134:135], v[120:121] op_sel:[1,0]
	v_pk_mul_f32 v[122:123], v[134:135], v[122:123] op_sel:[1,0]
	s_waitcnt lgkmcnt(0)
	v_sub_f32_e32 v101, v101, v128
	v_sub_f32_e32 v100, v100, v128
	v_lshl_add_u64 v[154:155], v[152:153], 0, v[158:159]
	v_lshl_add_u64 v[152:153], v[164:165], 0, v[158:159]
	v_sub_f32_e32 v103, v103, v128
	v_sub_f32_e32 v102, v102, v128
	v_pk_mul_f32 v[100:101], v[128:129], v[100:101] op_sel:[1,0]
	v_pk_mul_f32 v[102:103], v[128:129], v[102:103] op_sel:[1,0]
	v_sub_f32_e32 v69, v69, v130
	v_sub_f32_e32 v68, v68, v130
	v_sub_f32_e32 v71, v71, v130
	v_sub_f32_e32 v70, v70, v130
	v_pk_mul_f32 v[68:69], v[130:131], v[68:69] op_sel:[1,0]
	v_pk_mul_f32 v[70:71], v[130:131], v[70:71] op_sel:[1,0]
	v_lshl_add_u64 v[166:167], s[66:67], 0, v[166:167]
	v_sub_f32_e32 v17, v17, v136
	v_sub_f32_e32 v16, v16, v136
	v_pk_mul_f32 v[16:17], v[136:137], v[16:17] op_sel:[1,0]
	s_waitcnt vmcnt(0)
	v_pk_fma_f32 v[106:107], v[142:143], v[106:107], v[146:147]
	v_pk_fma_f32 v[104:105], v[140:141], v[104:105], v[144:145]
	v_pk_fma_f32 v[118:119], v[142:143], v[118:119], v[146:147]
	v_pk_fma_f32 v[116:117], v[140:141], v[116:117], v[144:145]
	v_pk_fma_f32 v[126:127], v[142:143], v[126:127], v[146:147]
	v_pk_fma_f32 v[124:125], v[140:141], v[124:125], v[144:145]
	v_cndmask_b32_e32 v107, v162, v107, vcc
	v_cndmask_b32_e32 v106, v162, v106, vcc
	v_cndmask_b32_e32 v105, v162, v105, vcc
	v_cndmask_b32_e32 v104, v162, v104, vcc
	v_pk_fma_f32 v[164:165], v[142:143], v[122:123], v[146:147]
	v_pk_fma_f32 v[168:169], v[140:141], v[120:121], v[144:145]
	v_cndmask_b32_e32 v119, v162, v119, vcc
	v_cndmask_b32_e32 v118, v162, v118, vcc
	v_cndmask_b32_e32 v117, v162, v117, vcc
	v_cndmask_b32_e32 v116, v162, v116, vcc
	v_cndmask_b32_e32 v123, v162, v127, vcc
	v_cndmask_b32_e32 v122, v162, v126, vcc
	v_cndmask_b32_e32 v121, v162, v125, vcc
	v_cndmask_b32_e32 v120, v162, v124, vcc
	global_store_dwordx4 v[156:157], v[104:107], off sc1
	global_store_dwordx4 v[154:155], v[116:119], off sc1
	global_store_dwordx4 v[152:153], v[120:123], off sc1
	v_add_u32_e32 v106, 0x80, v160
	v_ashrrev_i32_e32 v107, 31, v106
	v_pk_fma_f32 v[100:101], v[140:141], v[100:101], v[144:145]
	v_pk_fma_f32 v[102:103], v[142:143], v[102:103], v[146:147]
	v_cndmask_b32_e32 v117, v162, v101, vcc
	v_cndmask_b32_e32 v116, v162, v100, vcc
	v_lshlrev_b64 v[100:101], 12, v[106:107]
	v_cndmask_b32_e32 v118, v162, v102, vcc
	v_lshl_add_u64 v[100:101], s[66:67], 0, v[100:101]
	v_add_u32_e32 v102, 0x90, v160
	v_cndmask_b32_e32 v119, v162, v103, vcc
	v_lshl_add_u64 v[100:101], v[100:101], 0, v[158:159]
	v_ashrrev_i32_e32 v103, 31, v102
	v_pk_fma_f32 v[68:69], v[140:141], v[68:69], v[144:145]
	global_store_dwordx4 v[100:101], v[116:119], off sc1
	v_pk_fma_f32 v[70:71], v[142:143], v[70:71], v[146:147]
	v_add_u32_e32 v106, 0xa0, v160
	v_cndmask_b32_e32 v117, v162, v69, vcc
	v_cndmask_b32_e32 v116, v162, v68, vcc
	v_lshlrev_b64 v[68:69], 12, v[102:103]
	v_cndmask_b32_e32 v119, v162, v71, vcc
	v_cndmask_b32_e32 v118, v162, v70, vcc
	v_lshl_add_u64 v[102:103], s[66:67], 0, v[68:69]
	ds_read2_b64 v[68:71], v170 offset0:160 offset1:176
	v_lshl_add_u64 v[102:103], v[102:103], 0, v[158:159]
	v_ashrrev_i32_e32 v107, 31, v106
	global_store_dwordx4 v[102:103], v[116:119], off sc1
	v_cndmask_b32_e32 v127, v162, v165, vcc
	s_waitcnt lgkmcnt(0)
; #define PG8_LAS __attribute__((address_space(3)))
; __device__ __forceinline__ unsigned cvt_pk_bf16(float lo, float hi) { f32x2c_t v = {lo, hi}; bf16x2c_t b = __builtin_convertvector(v, bf16x2c_t); return __builtin_bit_cast(unsigned, b); }
;     __device__ __forceinline__ void fused(f32x4 (&acc)[2][2][4][2], const Unit& u, int wr, int wc, int fr, int fq, PG8_LAS unsigned char* lds, int wid, int lane) const {
;     ...
; #pragma unroll
;         for (int bj = 0; bj < 2; ++bj)
; #pragma unroll
;             for (int n = 0; n < 2; ++n) { const int c = col0 + bj * HALF + n * 16; const f32x4 g4 = *(const f32x4*)(gam + c), b4 = *(const f32x4*)(bet + c);
; #pragma unroll
;                 for (int ai = 0; ai < 2; ++ai)
; #pragma unroll
;                     for (int m = 0; m < 4; ++m) { const int r = ai * HALF + wr * 64 + m * 16 + fr; const f32x2v sr = S[r]; const size_t o = (size_t)(u.pm * BM + r) * ldc + c;
;                         f32x4 v = (acc[ai][bj][m][n] - sr.x) * sr.y * g4 + b4; if (bad) v = (f32x4){qnan, qnan, qnan, qnan};
;                         if (OUT_BF16) { u32x2v w; w.x = cvt_pk_bf16(v[0], v[1]); w.y = cvt_pk_bf16(v[2], v[3]); *(PG8_LAS u32x2v*)(lds + 16384 + r * 528 + (c - u.pn * BM) * 2) = w; }
;                         else *(f32x4*)((float*)out + o) = v; } }
	v_sub_f32_e32 v37, v37, v68
	v_sub_f32_e32 v36, v36, v68
	v_sub_f32_e32 v39, v39, v68
	v_sub_f32_e32 v38, v38, v68
	v_pk_mul_f32 v[36:37], v[68:69], v[36:37] op_sel:[1,0]
	v_pk_mul_f32 v[38:39], v[68:69], v[38:39] op_sel:[1,0]
	v_pk_fma_f32 v[36:37], v[140:141], v[36:37], v[144:145]
	v_pk_fma_f32 v[38:39], v[142:143], v[38:39], v[146:147]
	v_cndmask_b32_e32 v117, v162, v37, vcc
	v_cndmask_b32_e32 v116, v162, v36, vcc
	v_lshlrev_b64 v[36:37], 12, v[106:107]
	v_sub_f32_e32 v13, v13, v70
	v_sub_f32_e32 v12, v12, v70
	v_cndmask_b32_e32 v118, v162, v38, vcc
	v_lshl_add_u64 v[36:37], s[66:67], 0, v[36:37]
	v_add_u32_e32 v38, 0xb0, v160
	v_pk_mul_f32 v[12:13], v[70:71], v[12:13] op_sel:[1,0]
	v_cndmask_b32_e32 v119, v162, v39, vcc
	v_lshl_add_u64 v[36:37], v[36:37], 0, v[158:159]
	v_ashrrev_i32_e32 v39, 31, v38
	v_sub_f32_e32 v15, v15, v70
	v_sub_f32_e32 v14, v14, v70
	v_pk_fma_f32 v[12:13], v[140:141], v[12:13], v[144:145]
	global_store_dwordx4 v[36:37], v[116:119], off sc1
	v_pk_mul_f32 v[14:15], v[70:71], v[14:15] op_sel:[1,0]
	v_cndmask_b32_e32 v126, v162, v164, vcc
	v_cndmask_b32_e32 v117, v162, v13, vcc
	v_cndmask_b32_e32 v116, v162, v12, vcc
	v_lshlrev_b64 v[12:13], 12, v[38:39]
	v_pk_fma_f32 v[14:15], v[142:143], v[14:15], v[146:147]
	v_lshl_add_u64 v[12:13], s[66:67], 0, v[12:13]
	v_cndmask_b32_e32 v125, v162, v169, vcc
	v_cndmask_b32_e32 v124, v162, v168, vcc
	v_lshl_add_u64 v[104:105], v[166:167], 0, v[158:159]
	v_cndmask_b32_e32 v119, v162, v15, vcc
	v_cndmask_b32_e32 v118, v162, v14, vcc
	v_lshl_add_u64 v[12:13], v[12:13], 0, v[158:159]
	global_store_dwordx4 v[104:105], v[124:127], off sc1
	global_store_dwordx4 v[12:13], v[116:119], off sc1
	global_load_dwordx4 v[116:119], v[148:149], off offset:64
	s_nop 0
	global_load_dwordx4 v[120:123], v[150:151], off offset:64
	v_sub_f32_e32 v15, v75, v136
	v_sub_f32_e32 v14, v74, v136
	v_pk_mul_f32 v[14:15], v[136:137], v[14:15] op_sel:[1,0]
	v_sub_f32_e32 v39, v73, v136
	v_sub_f32_e32 v38, v72, v136
	v_pk_mul_f32 v[38:39], v[136:137], v[38:39] op_sel:[1,0]
	v_sub_f32_e32 v29, v29, v68
	v_sub_f32_e32 v28, v28, v68
	v_sub_f32_e32 v11, v11, v70
	v_sub_f32_e32 v10, v10, v70
	v_sub_f32_e32 v9, v9, v70
	v_sub_f32_e32 v8, v8, v70
	v_pk_mul_f32 v[28:29], v[68:69], v[28:29] op_sel:[1,0]
	v_pk_mul_f32 v[8:9], v[70:71], v[8:9] op_sel:[1,0]
	v_pk_mul_f32 v[10:11], v[70:71], v[10:11] op_sel:[1,0]
	v_sub_f32_e32 v25, v25, v68
	v_sub_f32_e32 v24, v24, v68
	v_sub_f32_e32 v7, v7, v70
	v_sub_f32_e32 v6, v6, v70
	v_sub_f32_e32 v5, v5, v70
	v_sub_f32_e32 v4, v4, v70
	v_pk_mul_f32 v[24:25], v[68:69], v[24:25] op_sel:[1,0]
	v_pk_mul_f32 v[4:5], v[70:71], v[4:5] op_sel:[1,0]
	v_pk_mul_f32 v[6:7], v[70:71], v[6:7] op_sel:[1,0]
	v_sub_f32_e32 v3, v3, v70
	v_sub_f32_e32 v2, v2, v70
	v_sub_f32_e32 v1, v1, v70
	v_sub_f32_e32 v0, v0, v70
	v_pk_mul_f32 v[0:1], v[70:71], v[0:1] op_sel:[1,0]
	v_pk_mul_f32 v[2:3], v[70:71], v[2:3] op_sel:[1,0]
	s_waitcnt vmcnt(0)
	v_pk_fma_f32 v[14:15], v[14:15], v[118:119], v[122:123]
	s_nop 0
	v_cndmask_b32_e32 v75, v162, v15, vcc
	v_cndmask_b32_e32 v74, v162, v14, vcc
	v_sub_f32_e32 v15, v91, v138
	v_sub_f32_e32 v14, v90, v138
	v_pk_fma_f32 v[38:39], v[38:39], v[116:117], v[120:121]
	v_pk_mul_f32 v[14:15], v[138:139], v[14:15] op_sel:[1,0]
	v_cndmask_b32_e32 v73, v162, v39, vcc
	v_cndmask_b32_e32 v72, v162, v38, vcc
	v_sub_f32_e32 v39, v89, v138
	v_sub_f32_e32 v38, v88, v138
	v_pk_fma_f32 v[14:15], v[14:15], v[118:119], v[122:123]
	global_store_dwordx4 v[156:157], v[72:75], off offset:64 sc1
	v_pk_mul_f32 v[38:39], v[138:139], v[38:39] op_sel:[1,0]
	v_pk_fma_f32 v[28:29], v[28:29], v[116:117], v[120:121]
	v_cndmask_b32_e32 v75, v162, v15, vcc
	v_cndmask_b32_e32 v74, v162, v14, vcc
	v_sub_f32_e32 v15, v111, v132
	v_sub_f32_e32 v14, v110, v132
	v_pk_fma_f32 v[38:39], v[38:39], v[116:117], v[120:121]
	v_pk_mul_f32 v[14:15], v[132:133], v[14:15] op_sel:[1,0]
	v_cndmask_b32_e32 v73, v162, v39, vcc
	v_cndmask_b32_e32 v72, v162, v38, vcc
	v_sub_f32_e32 v39, v109, v132
	v_sub_f32_e32 v38, v108, v132
	v_pk_fma_f32 v[14:15], v[14:15], v[118:119], v[122:123]
	global_store_dwordx4 v[154:155], v[72:75], off offset:64 sc1
	v_pk_mul_f32 v[38:39], v[132:133], v[38:39] op_sel:[1,0]
	v_pk_fma_f32 v[10:11], v[118:119], v[10:11], v[122:123]
	v_cndmask_b32_e32 v75, v162, v15, vcc
	v_cndmask_b32_e32 v74, v162, v14, vcc
	v_sub_f32_e32 v15, v115, v134
	v_sub_f32_e32 v14, v114, v134
	v_pk_fma_f32 v[38:39], v[38:39], v[116:117], v[120:121]
	v_pk_mul_f32 v[14:15], v[134:135], v[14:15] op_sel:[1,0]
	v_cndmask_b32_e32 v73, v162, v39, vcc
	v_cndmask_b32_e32 v72, v162, v38, vcc
	v_sub_f32_e32 v39, v113, v134
	v_sub_f32_e32 v38, v112, v134
	v_pk_fma_f32 v[14:15], v[14:15], v[118:119], v[122:123]
	global_store_dwordx4 v[152:153], v[72:75], off offset:64 sc1
	v_pk_mul_f32 v[38:39], v[134:135], v[38:39] op_sel:[1,0]
	v_pk_fma_f32 v[8:9], v[116:117], v[8:9], v[120:121]
	v_cndmask_b32_e32 v75, v162, v15, vcc
	v_cndmask_b32_e32 v74, v162, v14, vcc
	v_sub_f32_e32 v15, v99, v128
	v_sub_f32_e32 v14, v98, v128
	v_pk_fma_f32 v[38:39], v[38:39], v[116:117], v[120:121]
	v_pk_mul_f32 v[14:15], v[128:129], v[14:15] op_sel:[1,0]
	v_cndmask_b32_e32 v73, v162, v39, vcc
	v_cndmask_b32_e32 v72, v162, v38, vcc
	v_pk_fma_f32 v[14:15], v[14:15], v[118:119], v[122:123]
	global_store_dwordx4 v[104:105], v[72:75], off offset:64 sc1
	v_sub_f32_e32 v39, v97, v128
	v_sub_f32_e32 v38, v96, v128
	v_cndmask_b32_e32 v75, v162, v15, vcc
	v_cndmask_b32_e32 v74, v162, v14, vcc
	v_sub_f32_e32 v15, v67, v130
	v_sub_f32_e32 v14, v66, v130
	v_pk_mul_f32 v[38:39], v[128:129], v[38:39] op_sel:[1,0]
	v_pk_mul_f32 v[14:15], v[130:131], v[14:15] op_sel:[1,0]
; #define PG8_LAS __attribute__((address_space(3)))
; __device__ __forceinline__ unsigned cvt_pk_bf16(float lo, float hi) { f32x2c_t v = {lo, hi}; bf16x2c_t b = __builtin_convertvector(v, bf16x2c_t); return __builtin_bit_cast(unsigned, b); }
;     __device__ __forceinline__ void fused(f32x4 (&acc)[2][2][4][2], const Unit& u, int wr, int wc, int fr, int fq, PG8_LAS unsigned char* lds, int wid, int lane) const {
;     ...
; #pragma unroll
;         for (int bj = 0; bj < 2; ++bj)
; #pragma unroll
;             for (int n = 0; n < 2; ++n) { const int c = col0 + bj * HALF + n * 16; const f32x4 g4 = *(const f32x4*)(gam + c), b4 = *(const f32x4*)(bet + c);
; #pragma unroll
;                 for (int ai = 0; ai < 2; ++ai)
; #pragma unroll
;                     for (int m = 0; m < 4; ++m) { const int r = ai * HALF + wr * 64 + m * 16 + fr; const f32x2v sr = S[r]; const size_t o = (size_t)(u.pm * BM + r) * ldc + c;
;                         f32x4 v = (acc[ai][bj][m][n] - sr.x) * sr.y * g4 + b4; if (bad) v = (f32x4){qnan, qnan, qnan, qnan};
;                         if (OUT_BF16) { u32x2v w; w.x = cvt_pk_bf16(v[0], v[1]); w.y = cvt_pk_bf16(v[2], v[3]); *(PG8_LAS u32x2v*)(lds + 16384 + r * 528 + (c - u.pn * BM) * 2) = w; }
;                         else *(f32x4*)((float*)out + o) = v; } }
	v_pk_fma_f32 v[38:39], v[38:39], v[116:117], v[120:121]
	v_pk_fma_f32 v[14:15], v[14:15], v[118:119], v[122:123]
	v_cndmask_b32_e32 v73, v162, v39, vcc
	v_cndmask_b32_e32 v72, v162, v38, vcc
	v_sub_f32_e32 v39, v65, v130
	v_sub_f32_e32 v38, v64, v130
	v_cndmask_b32_e32 v67, v162, v15, vcc
	v_cndmask_b32_e32 v66, v162, v14, vcc
	v_sub_f32_e32 v15, v31, v68
	v_sub_f32_e32 v14, v30, v68
	v_pk_mul_f32 v[38:39], v[130:131], v[38:39] op_sel:[1,0]
	v_pk_mul_f32 v[14:15], v[68:69], v[14:15] op_sel:[1,0]
	v_pk_fma_f32 v[38:39], v[38:39], v[116:117], v[120:121]
	v_pk_fma_f32 v[14:15], v[14:15], v[118:119], v[122:123]
	v_cndmask_b32_e32 v65, v162, v39, vcc
	v_cndmask_b32_e32 v64, v162, v38, vcc
	v_cndmask_b32_e32 v31, v162, v15, vcc
	v_cndmask_b32_e32 v30, v162, v14, vcc
	v_cndmask_b32_e32 v29, v162, v29, vcc
	v_cndmask_b32_e32 v28, v162, v28, vcc
	v_cndmask_b32_e32 v11, v162, v11, vcc
	v_cndmask_b32_e32 v10, v162, v10, vcc
	v_cndmask_b32_e32 v9, v162, v9, vcc
	v_cndmask_b32_e32 v8, v162, v8, vcc
	global_store_dwordx4 v[100:101], v[72:75], off offset:64 sc1
	global_store_dwordx4 v[102:103], v[64:67], off offset:64 sc1
	global_store_dwordx4 v[36:37], v[28:31], off offset:64 sc1
	global_store_dwordx4 v[12:13], v[8:11], off offset:64 sc1
	global_load_dwordx4 v[8:11], v[148:149], off offset:512
	s_nop 0
	global_load_dwordx4 v[28:31], v[150:151], off offset:512
	v_sub_f32_e32 v15, v43, v136
	v_sub_f32_e32 v14, v42, v136
	v_sub_f32_e32 v39, v41, v136
	v_sub_f32_e32 v38, v40, v136
	v_pk_mul_f32 v[38:39], v[136:137], v[38:39] op_sel:[1,0]
	v_pk_mul_f32 v[14:15], v[136:137], v[14:15] op_sel:[1,0]
	s_waitcnt vmcnt(0)
	v_pk_fma_f32 v[38:39], v[38:39], v[8:9], v[28:29]
	v_pk_fma_f32 v[14:15], v[14:15], v[10:11], v[30:31]
	v_cndmask_b32_e32 v39, v162, v39, vcc
	v_cndmask_b32_e32 v41, v162, v15, vcc
	v_cndmask_b32_e32 v40, v162, v14, vcc
	v_cndmask_b32_e32 v38, v162, v38, vcc
	global_store_dwordx4 v[156:157], v[38:41], off offset:512 sc1
	v_sub_f32_e32 v15, v55, v138
	v_sub_f32_e32 v14, v54, v138
	v_sub_f32_e32 v39, v53, v138
	v_sub_f32_e32 v38, v52, v138
	v_pk_mul_f32 v[38:39], v[138:139], v[38:39] op_sel:[1,0]
	v_pk_mul_f32 v[14:15], v[138:139], v[14:15] op_sel:[1,0]
	v_pk_fma_f32 v[38:39], v[38:39], v[8:9], v[28:29]
	v_pk_fma_f32 v[14:15], v[14:15], v[10:11], v[30:31]
	v_cndmask_b32_e32 v39, v162, v39, vcc
	v_cndmask_b32_e32 v41, v162, v15, vcc
	v_cndmask_b32_e32 v40, v162, v14, vcc
	v_cndmask_b32_e32 v38, v162, v38, vcc
	global_store_dwordx4 v[154:155], v[38:41], off offset:512 sc1
	v_sub_f32_e32 v15, v79, v132
	v_sub_f32_e32 v14, v78, v132
	v_sub_f32_e32 v39, v77, v132
	v_sub_f32_e32 v38, v76, v132
	v_pk_mul_f32 v[38:39], v[132:133], v[38:39] op_sel:[1,0]
	v_pk_mul_f32 v[14:15], v[132:133], v[14:15] op_sel:[1,0]
	v_pk_fma_f32 v[38:39], v[38:39], v[8:9], v[28:29]
	v_pk_fma_f32 v[14:15], v[14:15], v[10:11], v[30:31]
	v_cndmask_b32_e32 v39, v162, v39, vcc
	v_cndmask_b32_e32 v41, v162, v15, vcc
	v_cndmask_b32_e32 v40, v162, v14, vcc
	v_cndmask_b32_e32 v38, v162, v38, vcc
	v_sub_f32_e32 v15, v95, v134
	v_sub_f32_e32 v14, v94, v134
	global_store_dwordx4 v[152:153], v[38:41], off offset:512 sc1
	v_pk_mul_f32 v[14:15], v[134:135], v[14:15] op_sel:[1,0]
	v_pk_fma_f32 v[24:25], v[24:25], v[8:9], v[28:29]
	v_sub_f32_e32 v39, v93, v134
	v_sub_f32_e32 v38, v92, v134
	v_pk_mul_f32 v[38:39], v[134:135], v[38:39] op_sel:[1,0]
	v_pk_fma_f32 v[14:15], v[14:15], v[10:11], v[30:31]
	v_pk_fma_f32 v[38:39], v[38:39], v[8:9], v[28:29]
	v_cndmask_b32_e32 v41, v162, v15, vcc
	v_cndmask_b32_e32 v40, v162, v14, vcc
	v_sub_f32_e32 v15, v87, v128
	v_sub_f32_e32 v14, v86, v128
	v_cndmask_b32_e32 v39, v162, v39, vcc
	v_cndmask_b32_e32 v38, v162, v38, vcc
	v_pk_mul_f32 v[14:15], v[128:129], v[14:15] op_sel:[1,0]
	global_store_dwordx4 v[104:105], v[38:41], off offset:512 sc1
	v_pk_fma_f32 v[14:15], v[14:15], v[10:11], v[30:31]
	v_pk_fma_f32 v[6:7], v[6:7], v[10:11], v[30:31]
	v_sub_f32_e32 v39, v85, v128
	v_sub_f32_e32 v38, v84, v128
	v_pk_mul_f32 v[38:39], v[128:129], v[38:39] op_sel:[1,0]
	v_cndmask_b32_e32 v41, v162, v15, vcc
	v_cndmask_b32_e32 v40, v162, v14, vcc
	v_sub_f32_e32 v15, v59, v130
	v_sub_f32_e32 v14, v58, v130
	v_pk_fma_f32 v[38:39], v[38:39], v[8:9], v[28:29]
	v_pk_mul_f32 v[14:15], v[130:131], v[14:15] op_sel:[1,0]
	v_cndmask_b32_e32 v39, v162, v39, vcc
	v_cndmask_b32_e32 v38, v162, v38, vcc
	v_pk_fma_f32 v[14:15], v[14:15], v[10:11], v[30:31]
	global_store_dwordx4 v[100:101], v[38:41], off offset:512 sc1
	v_pk_fma_f32 v[4:5], v[4:5], v[8:9], v[28:29]
	v_cndmask_b32_e32 v25, v162, v25, vcc
	v_sub_f32_e32 v39, v57, v130
	v_sub_f32_e32 v38, v56, v130
	v_cndmask_b32_e32 v41, v162, v15, vcc
	v_cndmask_b32_e32 v40, v162, v14, vcc
	v_sub_f32_e32 v15, v27, v68
	v_sub_f32_e32 v14, v26, v68
	v_pk_mul_f32 v[38:39], v[130:131], v[38:39] op_sel:[1,0]
	v_pk_mul_f32 v[14:15], v[68:69], v[14:15] op_sel:[1,0]
	v_pk_fma_f32 v[38:39], v[38:39], v[8:9], v[28:29]
	v_pk_fma_f32 v[14:15], v[14:15], v[10:11], v[30:31]
	v_cndmask_b32_e32 v39, v162, v39, vcc
	v_cndmask_b32_e32 v38, v162, v38, vcc
	v_cndmask_b32_e32 v27, v162, v15, vcc
	v_cndmask_b32_e32 v26, v162, v14, vcc
	v_cndmask_b32_e32 v24, v162, v24, vcc
	v_cndmask_b32_e32 v7, v162, v7, vcc
	v_cndmask_b32_e32 v6, v162, v6, vcc
	v_cndmask_b32_e32 v5, v162, v5, vcc
	v_cndmask_b32_e32 v4, v162, v4, vcc
	global_store_dwordx4 v[102:103], v[38:41], off offset:512 sc1
	global_store_dwordx4 v[36:37], v[24:27], off offset:512 sc1
	global_store_dwordx4 v[12:13], v[4:7], off offset:512 sc1
	global_load_dwordx4 v[4:7], v[148:149], off offset:576
	s_nop 0
	global_load_dwordx4 v[8:11], v[150:151], off offset:576
	v_sub_f32_e32 v15, v19, v136
	v_sub_f32_e32 v14, v18, v136
	v_pk_mul_f32 v[14:15], v[136:137], v[14:15] op_sel:[1,0]
	s_waitcnt vmcnt(0)
; #define PG8_LAS __attribute__((address_space(3)))
; __device__ __forceinline__ unsigned cvt_pk_bf16(float lo, float hi) { f32x2c_t v = {lo, hi}; bf16x2c_t b = __builtin_convertvector(v, bf16x2c_t); return __builtin_bit_cast(unsigned, b); }
;     __device__ __forceinline__ void fused(f32x4 (&acc)[2][2][4][2], const Unit& u, int wr, int wc, int fr, int fq, PG8_LAS unsigned char* lds, int wid, int lane) const {
;     ...
; #pragma unroll
;         for (int bj = 0; bj < 2; ++bj)
; #pragma unroll
;             for (int n = 0; n < 2; ++n) { const int c = col0 + bj * HALF + n * 16; const f32x4 g4 = *(const f32x4*)(gam + c), b4 = *(const f32x4*)(bet + c);
; #pragma unroll
;                 for (int ai = 0; ai < 2; ++ai)
; #pragma unroll
;                     for (int m = 0; m < 4; ++m) { const int r = ai * HALF + wr * 64 + m * 16 + fr; const f32x2v sr = S[r]; const size_t o = (size_t)(u.pm * BM + r) * ldc + c;
;                         f32x4 v = (acc[ai][bj][m][n] - sr.x) * sr.y * g4 + b4; if (bad) v = (f32x4){qnan, qnan, qnan, qnan};
;                         if (OUT_BF16) { u32x2v w; w.x = cvt_pk_bf16(v[0], v[1]); w.y = cvt_pk_bf16(v[2], v[3]); *(PG8_LAS u32x2v*)(lds + 16384 + r * 528 + (c - u.pn * BM) * 2) = w; }
;                         else *(f32x4*)((float*)out + o) = v; } }
	v_pk_fma_f32 v[18:19], v[16:17], v[4:5], v[8:9]
	v_pk_fma_f32 v[14:15], v[14:15], v[6:7], v[10:11]
	v_pk_fma_f32 v[2:3], v[2:3], v[6:7], v[10:11]
	v_cndmask_b32_e32 v17, v162, v15, vcc
	v_cndmask_b32_e32 v16, v162, v14, vcc
	v_cndmask_b32_e32 v15, v162, v19, vcc
	v_cndmask_b32_e32 v14, v162, v18, vcc
	global_store_dwordx4 v[156:157], v[14:17], off offset:576 sc1
	v_pk_fma_f32 v[0:1], v[0:1], v[4:5], v[8:9]
	v_cndmask_b32_e32 v3, v162, v3, vcc
	v_sub_f32_e32 v15, v35, v138
	v_sub_f32_e32 v14, v34, v138
	v_sub_f32_e32 v17, v33, v138
	v_sub_f32_e32 v16, v32, v138
	v_pk_mul_f32 v[16:17], v[138:139], v[16:17] op_sel:[1,0]
	v_pk_mul_f32 v[14:15], v[138:139], v[14:15] op_sel:[1,0]
	v_pk_fma_f32 v[18:19], v[16:17], v[4:5], v[8:9]
	v_pk_fma_f32 v[14:15], v[14:15], v[6:7], v[10:11]
	v_cndmask_b32_e32 v2, v162, v2, vcc
	v_cndmask_b32_e32 v17, v162, v15, vcc
	v_cndmask_b32_e32 v16, v162, v14, vcc
	v_cndmask_b32_e32 v15, v162, v19, vcc
	v_cndmask_b32_e32 v14, v162, v18, vcc
	global_store_dwordx4 v[154:155], v[14:17], off offset:576 sc1
	v_cndmask_b32_e32 v1, v162, v1, vcc
	v_cndmask_b32_e32 v0, v162, v0, vcc
	v_sub_f32_e32 v15, v47, v132
	v_sub_f32_e32 v14, v46, v132
	v_sub_f32_e32 v17, v45, v132
	v_sub_f32_e32 v16, v44, v132
	v_pk_mul_f32 v[16:17], v[132:133], v[16:17] op_sel:[1,0]
	v_pk_mul_f32 v[14:15], v[132:133], v[14:15] op_sel:[1,0]
	v_pk_fma_f32 v[18:19], v[16:17], v[4:5], v[8:9]
	v_pk_fma_f32 v[14:15], v[14:15], v[6:7], v[10:11]
	s_nop 0
	v_cndmask_b32_e32 v17, v162, v15, vcc
	v_cndmask_b32_e32 v16, v162, v14, vcc
	v_cndmask_b32_e32 v15, v162, v19, vcc
	v_cndmask_b32_e32 v14, v162, v18, vcc
	global_store_dwordx4 v[152:153], v[14:17], off offset:576 sc1
	s_nop 1
	v_sub_f32_e32 v15, v63, v134
	v_sub_f32_e32 v14, v62, v134
	v_sub_f32_e32 v17, v61, v134
	v_sub_f32_e32 v16, v60, v134
	v_pk_mul_f32 v[16:17], v[134:135], v[16:17] op_sel:[1,0]
	v_pk_mul_f32 v[14:15], v[134:135], v[14:15] op_sel:[1,0]
	v_pk_fma_f32 v[18:19], v[16:17], v[4:5], v[8:9]
	v_pk_fma_f32 v[14:15], v[14:15], v[6:7], v[10:11]
	s_nop 0
	v_cndmask_b32_e32 v17, v162, v15, vcc
	v_cndmask_b32_e32 v16, v162, v14, vcc
	v_cndmask_b32_e32 v15, v162, v19, vcc
	v_cndmask_b32_e32 v14, v162, v18, vcc
	global_store_dwordx4 v[104:105], v[14:17], off offset:576 sc1
	global_store_dwordx4 v[12:13], v[0:3], off offset:576 sc1
	s_nop 0
	v_sub_f32_e32 v15, v83, v128
	v_sub_f32_e32 v14, v82, v128
	v_sub_f32_e32 v17, v81, v128
	v_sub_f32_e32 v16, v80, v128
	v_pk_mul_f32 v[16:17], v[128:129], v[16:17] op_sel:[1,0]
	v_pk_mul_f32 v[14:15], v[128:129], v[14:15] op_sel:[1,0]
	v_pk_fma_f32 v[18:19], v[16:17], v[4:5], v[8:9]
	v_pk_fma_f32 v[14:15], v[14:15], v[6:7], v[10:11]
	s_nop 0
	v_cndmask_b32_e32 v17, v162, v15, vcc
	v_cndmask_b32_e32 v16, v162, v14, vcc
	v_cndmask_b32_e32 v15, v162, v19, vcc
	v_cndmask_b32_e32 v14, v162, v18, vcc
	global_store_dwordx4 v[100:101], v[14:17], off offset:576 sc1
	s_nop 1
	v_sub_f32_e32 v15, v51, v130
	v_sub_f32_e32 v14, v50, v130
	v_sub_f32_e32 v17, v49, v130
	v_sub_f32_e32 v16, v48, v130
	v_pk_mul_f32 v[16:17], v[130:131], v[16:17] op_sel:[1,0]
	v_pk_mul_f32 v[14:15], v[130:131], v[14:15] op_sel:[1,0]
	v_pk_fma_f32 v[18:19], v[16:17], v[4:5], v[8:9]
	v_pk_fma_f32 v[14:15], v[14:15], v[6:7], v[10:11]
	s_nop 0
	v_cndmask_b32_e32 v17, v162, v15, vcc
	v_cndmask_b32_e32 v16, v162, v14, vcc
	v_cndmask_b32_e32 v15, v162, v19, vcc
	v_cndmask_b32_e32 v14, v162, v18, vcc
	global_store_dwordx4 v[102:103], v[14:17], off offset:576 sc1
	s_nop 1
	v_sub_f32_e32 v15, v23, v68
	v_sub_f32_e32 v14, v22, v68
	v_sub_f32_e32 v17, v21, v68
	v_sub_f32_e32 v16, v20, v68
	v_pk_mul_f32 v[16:17], v[68:69], v[16:17] op_sel:[1,0]
	v_pk_mul_f32 v[14:15], v[68:69], v[14:15] op_sel:[1,0]
	v_pk_fma_f32 v[18:19], v[16:17], v[4:5], v[8:9]
	v_pk_fma_f32 v[14:15], v[14:15], v[6:7], v[10:11]
	s_nop 0
	v_cndmask_b32_e32 v17, v162, v15, vcc
	v_cndmask_b32_e32 v16, v162, v14, vcc
	v_cndmask_b32_e32 v15, v162, v19, vcc
	v_cndmask_b32_e32 v14, v162, v18, vcc
	global_store_dwordx4 v[36:37], v[14:17], off offset:576 sc1
